# stagger2
# baseline (speedup 1.0000x reference)
.Lsrt_loop_b:
	v_mfma_f32_16x16x32_bf16 v[30:33], v[60:63], v[64:67], v[30:33]
	v_mfma_f32_16x16x32_bf16 v[14:17], v[68:71], v[64:67], v[14:17]
	v_mfma_f32_16x16x32_bf16 v[26:29], v[60:63], v[88:91], v[26:29]
	v_mfma_f32_16x16x32_bf16 v[10:13], v[68:71], v[88:91], v[10:13]
	v_mfma_f32_16x16x32_bf16 v[22:25], v[60:63], v[92:95], v[22:25]
	v_mfma_f32_16x16x32_bf16 v[6:9], v[68:71], v[92:95], v[6:9]
	v_mfma_f32_16x16x32_bf16 v[18:21], v[60:63], v[96:99], v[18:21]
	v_mfma_f32_16x16x32_bf16 v[2:5], v[68:71], v[96:99], v[2:5]
	s_waitcnt vmcnt(4)
	ds_write_b128 v57, v[46:49]
	ds_write_b128 v57, v[42:45] offset:16
	ds_write_b128 v57, v[38:41] offset:20480
	ds_write_b128 v57, v[34:37] offset:20496
	ds_read_b128 v[176:179], v59 offset:61440
	ds_read_b128 v[180:183], v58 offset:40960
	ds_read_b128 v[184:187], v59 offset:64000
	ds_read_b128 v[188:191], v58 offset:43520
	ds_read_b128 v[192:195], v58 offset:46080
	ds_read_b128 v[196:199], v58 offset:48640
	ds_read_b128 v[200:203], v59 offset:61504
	ds_read_b128 v[204:207], v58 offset:41024
	ds_read_b128 v[208:211], v59 offset:64064
	ds_read_b128 v[224:227], v58 offset:43584
	ds_read_b128 v[228:231], v58 offset:46144
	ds_read_b128 v[232:235], v58 offset:48704
	s_add_i32 s14, s6, 4
	s_add_i32 s22, s64, -1
	s_min_u32 s14, s14, s22
	s_lshl_b32 s22, s14, 7
	v_mfma_f32_16x16x32_bf16 v[30:33], v[100:103], v[104:107], v[30:33]
	v_mfma_f32_16x16x32_bf16 v[14:17], v[108:111], v[104:107], v[14:17]
	v_mfma_f32_16x16x32_bf16 v[26:29], v[100:103], v[112:115], v[26:29]
	v_mfma_f32_16x16x32_bf16 v[10:13], v[108:111], v[112:115], v[10:13]
	v_mfma_f32_16x16x32_bf16 v[22:25], v[100:103], v[116:119], v[22:25]
	v_mfma_f32_16x16x32_bf16 v[6:9], v[108:111], v[116:119], v[6:9]
	v_mfma_f32_16x16x32_bf16 v[18:21], v[100:103], v[120:123], v[18:21]
	v_mfma_f32_16x16x32_bf16 v[2:5], v[108:111], v[120:123], v[2:5]
	s_waitcnt lgkmcnt(12)
	v_lshl_add_u64 v[124:125], v[50:51], 0, s[22:23]
	v_lshl_add_u64 v[126:127], v[52:53], 0, s[22:23]
	global_load_dwordx4 v[46:49], v[124:125], off
	global_load_dwordx4 v[42:45], v[124:125], off offset:16
	global_load_dwordx4 v[38:41], v[126:127], off
	global_load_dwordx4 v[34:37], v[126:127], off offset:16
	s_waitcnt lgkmcnt(0)
	s_barrier
	v_mfma_f32_16x16x32_bf16 v[30:33], v[176:179], v[180:183], v[30:33]
	v_mfma_f32_16x16x32_bf16 v[14:17], v[184:187], v[180:183], v[14:17]
	v_mfma_f32_16x16x32_bf16 v[26:29], v[176:179], v[188:191], v[26:29]
	v_mfma_f32_16x16x32_bf16 v[10:13], v[184:187], v[188:191], v[10:13]
	v_mfma_f32_16x16x32_bf16 v[22:25], v[176:179], v[192:195], v[22:25]
	v_mfma_f32_16x16x32_bf16 v[6:9], v[184:187], v[192:195], v[6:9]
	v_mfma_f32_16x16x32_bf16 v[18:21], v[176:179], v[196:199], v[18:21]
	v_mfma_f32_16x16x32_bf16 v[2:5], v[184:187], v[196:199], v[2:5]
	s_waitcnt vmcnt(4)
	ds_write_b128 v57, v[84:87] offset:40960
	ds_write_b128 v57, v[80:83] offset:40976
	ds_write_b128 v57, v[76:79] offset:61440
	ds_write_b128 v57, v[72:75] offset:61456
	ds_read_b128 v[60:63], v59 offset:20480
	ds_read_b128 v[64:67], v58
	ds_read_b128 v[68:71], v59 offset:23040
	ds_read_b128 v[88:91], v58 offset:2560
	ds_read_b128 v[92:95], v58 offset:5120
	ds_read_b128 v[96:99], v58 offset:7680
	ds_read_b128 v[100:103], v59 offset:20544
	ds_read_b128 v[104:107], v58 offset:64
	ds_read_b128 v[108:111], v59 offset:23104
	ds_read_b128 v[112:115], v58 offset:2624
	ds_read_b128 v[116:119], v58 offset:5184
	ds_read_b128 v[120:123], v58 offset:7744
	s_add_i32 s14, s6, 5
	s_add_i32 s22, s64, -1
	s_min_u32 s14, s14, s22
	s_lshl_b32 s22, s14, 7
	v_mfma_f32_16x16x32_bf16 v[30:33], v[200:203], v[204:207], v[30:33]
	v_mfma_f32_16x16x32_bf16 v[14:17], v[208:211], v[204:207], v[14:17]
	v_mfma_f32_16x16x32_bf16 v[26:29], v[200:203], v[224:227], v[26:29]
	v_mfma_f32_16x16x32_bf16 v[10:13], v[208:211], v[224:227], v[10:13]
	v_mfma_f32_16x16x32_bf16 v[22:25], v[200:203], v[228:231], v[22:25]
	v_mfma_f32_16x16x32_bf16 v[6:9], v[208:211], v[228:231], v[6:9]
	v_mfma_f32_16x16x32_bf16 v[18:21], v[200:203], v[232:235], v[18:21]
	v_mfma_f32_16x16x32_bf16 v[2:5], v[208:211], v[232:235], v[2:5]
	s_waitcnt lgkmcnt(12)
	v_lshl_add_u64 v[124:125], v[50:51], 0, s[22:23]
	v_lshl_add_u64 v[126:127], v[52:53], 0, s[22:23]
	global_load_dwordx4 v[84:87], v[124:125], off
	global_load_dwordx4 v[80:83], v[124:125], off offset:16
	global_load_dwordx4 v[76:79], v[126:127], off
	global_load_dwordx4 v[72:75], v[126:127], off offset:16
	s_waitcnt lgkmcnt(0)
	s_barrier
	s_add_i32 s6, s6, 2
	s_cmp_lt_u32 s6, s64
	s_cbranch_scc1 .Lsrt_loop_b
